# conditioning set-up: 36 silu staging loads issued together (was one load per vmcnt(0)); stacked on epilogue hoist, nt input streams, XCD-local seams
# baseline (speedup 1.0000x reference)
; __device__ __forceinline__ void ada_phase(LAS unsigned char* lds, const float* c, const float* c_ctx, const float* ada_w, const float* ada_b, float* mods, int G, int bid, int tid, int item0, int item1) {
;     ...
;     for (int idx = tid; idx < 9 * D; idx += NTHR) { const int r = idx / D, k = idx % D; const float v = (r < 8) ? c[r * D + k] : c_ctx[k]; sT[k * 9 + r] = v / (1.0f + __expf(-v)); }
.LBB0_371:
	s_andn2_b64 vcc, exec, s[8:9]
	s_cbranch_vccnz .LBB0_551
	v_mov_b32_e32 v1, v165
	s_waitcnt vmcnt(0)
	s_barrier
	s_load_dwordx4 s[8:11], s[0:1], 0x18
	s_movk_i32 s6, 0x4800
	v_readfirstlane_b32 s18, v1
	v_cmp_gt_i32_e32 vcc, s6, v1
	s_and_saveexec_b64 s[6:7], vcc
	s_cbranch_execz .LBB0_379
	s_load_dwordx2 s[20:21], s[0:1], 0x8
	v_mul_u32_u24_e32 v2, 36, v1
	v_lshlrev_b32_e32 v3, 2, v1
	s_waitcnt lgkmcnt(0)
	s_mov_b64 s[12:13], s[20:21]
	global_load_dword v20, v3, s[12:13]
	s_add_u32 s12, s12, 0x800
	s_addc_u32 s13, s13, 0
	global_load_dword v21, v3, s[12:13]
	s_add_u32 s12, s12, 0x800
	s_addc_u32 s13, s13, 0
	global_load_dword v22, v3, s[12:13]
	s_add_u32 s12, s12, 0x800
	s_addc_u32 s13, s13, 0
	global_load_dword v23, v3, s[12:13]
	s_add_u32 s12, s12, 0x800
	s_addc_u32 s13, s13, 0
	global_load_dword v24, v3, s[12:13]
	s_add_u32 s12, s12, 0x800
	s_addc_u32 s13, s13, 0
	global_load_dword v25, v3, s[12:13]
	s_add_u32 s12, s12, 0x800
	s_addc_u32 s13, s13, 0
	global_load_dword v26, v3, s[12:13]
	s_add_u32 s12, s12, 0x800
	s_addc_u32 s13, s13, 0
	global_load_dword v27, v3, s[12:13]
	s_add_u32 s12, s12, 0x800
	s_addc_u32 s13, s13, 0
	global_load_dword v28, v3, s[12:13]
	s_add_u32 s12, s12, 0x800
	s_addc_u32 s13, s13, 0
	global_load_dword v29, v3, s[12:13]
	s_add_u32 s12, s12, 0x800
	s_addc_u32 s13, s13, 0
	global_load_dword v30, v3, s[12:13]
	s_add_u32 s12, s12, 0x800
	s_addc_u32 s13, s13, 0
	global_load_dword v31, v3, s[12:13]
	s_add_u32 s12, s12, 0x800
	s_addc_u32 s13, s13, 0
	global_load_dword v32, v3, s[12:13]
	s_add_u32 s12, s12, 0x800
	s_addc_u32 s13, s13, 0
	global_load_dword v33, v3, s[12:13]
	s_add_u32 s12, s12, 0x800
	s_addc_u32 s13, s13, 0
	global_load_dword v34, v3, s[12:13]
	s_add_u32 s12, s12, 0x800
	s_addc_u32 s13, s13, 0
	global_load_dword v35, v3, s[12:13]
	s_add_u32 s12, s12, 0x800
	s_addc_u32 s13, s13, 0
	global_load_dword v36, v3, s[12:13]
	s_add_u32 s12, s12, 0x800
	s_addc_u32 s13, s13, 0
	global_load_dword v37, v3, s[12:13]
	s_add_u32 s12, s12, 0x800
	s_addc_u32 s13, s13, 0
	global_load_dword v38, v3, s[12:13]
	s_add_u32 s12, s12, 0x800
	s_addc_u32 s13, s13, 0
	global_load_dword v39, v3, s[12:13]
	s_add_u32 s12, s12, 0x800
	s_addc_u32 s13, s13, 0
	global_load_dword v40, v3, s[12:13]
	s_add_u32 s12, s12, 0x800
	s_addc_u32 s13, s13, 0
	global_load_dword v41, v3, s[12:13]
	s_add_u32 s12, s12, 0x800
	s_addc_u32 s13, s13, 0
	global_load_dword v42, v3, s[12:13]
	s_add_u32 s12, s12, 0x800
	s_addc_u32 s13, s13, 0
	global_load_dword v43, v3, s[12:13]
	s_add_u32 s12, s12, 0x800
	s_addc_u32 s13, s13, 0
	global_load_dword v44, v3, s[12:13]
	s_add_u32 s12, s12, 0x800
	s_addc_u32 s13, s13, 0
	global_load_dword v45, v3, s[12:13]
	s_add_u32 s12, s12, 0x800
	s_addc_u32 s13, s13, 0
	global_load_dword v46, v3, s[12:13]
	s_add_u32 s12, s12, 0x800
	s_addc_u32 s13, s13, 0
	global_load_dword v47, v3, s[12:13]
	s_add_u32 s12, s12, 0x800
	s_addc_u32 s13, s13, 0
	global_load_dword v48, v3, s[12:13]
	s_add_u32 s12, s12, 0x800
	s_addc_u32 s13, s13, 0
	global_load_dword v49, v3, s[12:13]
	s_add_u32 s12, s12, 0x800
	s_addc_u32 s13, s13, 0
	global_load_dword v50, v3, s[12:13]
	s_add_u32 s12, s12, 0x800
	s_addc_u32 s13, s13, 0
	global_load_dword v51, v3, s[12:13]
	s_add_u32 s12, s12, 0x800
	s_addc_u32 s13, s13, 0
	s_mov_b64 s[12:13], s[8:9]
	global_load_dword v52, v3, s[12:13]
	s_add_u32 s12, s12, 0x800
	s_addc_u32 s13, s13, 0
	global_load_dword v53, v3, s[12:13]
	s_add_u32 s12, s12, 0x800
	s_addc_u32 s13, s13, 0
	global_load_dword v54, v3, s[12:13]
	s_add_u32 s12, s12, 0x800
	s_addc_u32 s13, s13, 0
	global_load_dword v55, v3, s[12:13]
	s_waitcnt vmcnt(35)
	v_mul_f32_e32 v5, 0xbfb8aa3b, v20
	v_exp_f32_e32 v5, v5
	s_nop 0
	v_add_f32_e32 v5, 1.0, v5
	v_div_scale_f32 v8, s[14:15], v5, v5, v20
	v_rcp_f32_e32 v9, v8
	s_nop 0
	v_fma_f32 v10, -v8, v9, 1.0
	v_fmac_f32_e32 v9, v10, v9
	v_div_scale_f32 v10, vcc, v20, v5, v20
	v_mul_f32_e32 v11, v10, v9
	v_fma_f32 v12, -v8, v11, v10
	v_fmac_f32_e32 v11, v12, v9
	v_fma_f32 v8, -v8, v11, v10
	v_div_fmas_f32 v8, v8, v9, v11
	v_div_fixup_f32 v4, v8, v5, v20
	ds_write_b32 v2, v4
	s_waitcnt vmcnt(34)
	v_mul_f32_e32 v5, 0xbfb8aa3b, v21
	v_exp_f32_e32 v5, v5
	s_nop 0
	v_add_f32_e32 v5, 1.0, v5
	v_div_scale_f32 v8, s[14:15], v5, v5, v21
	v_rcp_f32_e32 v9, v8
	s_nop 0
	v_fma_f32 v10, -v8, v9, 1.0
	v_fmac_f32_e32 v9, v10, v9
	v_div_scale_f32 v10, vcc, v21, v5, v21
	v_mul_f32_e32 v11, v10, v9
	v_fma_f32 v12, -v8, v11, v10
	v_fmac_f32_e32 v11, v12, v9
	v_fma_f32 v8, -v8, v11, v10
	v_div_fmas_f32 v8, v8, v9, v11
	v_div_fixup_f32 v4, v8, v5, v21
	ds_write_b32 v2, v4 offset:18432
	s_waitcnt vmcnt(33)
	v_mul_f32_e32 v5, 0xbfb8aa3b, v22
	v_exp_f32_e32 v5, v5
	s_nop 0
	v_add_f32_e32 v5, 1.0, v5
	v_div_scale_f32 v8, s[14:15], v5, v5, v22
	v_rcp_f32_e32 v9, v8
	s_nop 0
	v_fma_f32 v10, -v8, v9, 1.0
	v_fmac_f32_e32 v9, v10, v9
	v_div_scale_f32 v10, vcc, v22, v5, v22
	v_mul_f32_e32 v11, v10, v9
	v_fma_f32 v12, -v8, v11, v10
	v_fmac_f32_e32 v11, v12, v9
	v_fma_f32 v8, -v8, v11, v10
	v_div_fmas_f32 v8, v8, v9, v11
	v_div_fixup_f32 v4, v8, v5, v22
	ds_write_b32 v2, v4 offset:36864
	s_waitcnt vmcnt(32)
	v_mul_f32_e32 v5, 0xbfb8aa3b, v23
	v_exp_f32_e32 v5, v5
	s_nop 0
	v_add_f32_e32 v5, 1.0, v5
	v_div_scale_f32 v8, s[14:15], v5, v5, v23
	v_rcp_f32_e32 v9, v8
	s_nop 0
	v_fma_f32 v10, -v8, v9, 1.0
	v_fmac_f32_e32 v9, v10, v9
	v_div_scale_f32 v10, vcc, v23, v5, v23
	v_mul_f32_e32 v11, v10, v9
	v_fma_f32 v12, -v8, v11, v10
	v_fmac_f32_e32 v11, v12, v9
	v_fma_f32 v8, -v8, v11, v10
	v_div_fmas_f32 v8, v8, v9, v11
	v_div_fixup_f32 v4, v8, v5, v23
	ds_write_b32 v2, v4 offset:55296
	s_waitcnt vmcnt(31)
; __device__ __forceinline__ void ada_phase(LAS unsigned char* lds, const float* c, const float* c_ctx, const float* ada_w, const float* ada_b, float* mods, int G, int bid, int tid, int item0, int item1) {
;     ...
;     for (int idx = tid; idx < 9 * D; idx += NTHR) { const int r = idx / D, k = idx % D; const float v = (r < 8) ? c[r * D + k] : c_ctx[k]; sT[k * 9 + r] = v / (1.0f + __expf(-v)); }
	v_mul_f32_e32 v5, 0xbfb8aa3b, v24
	v_exp_f32_e32 v5, v5
	s_nop 0
	v_add_f32_e32 v5, 1.0, v5
	v_div_scale_f32 v8, s[14:15], v5, v5, v24
	v_rcp_f32_e32 v9, v8
	s_nop 0
	v_fma_f32 v10, -v8, v9, 1.0
	v_fmac_f32_e32 v9, v10, v9
	v_div_scale_f32 v10, vcc, v24, v5, v24
	v_mul_f32_e32 v11, v10, v9
	v_fma_f32 v12, -v8, v11, v10
	v_fmac_f32_e32 v11, v12, v9
	v_fma_f32 v8, -v8, v11, v10
	v_div_fmas_f32 v8, v8, v9, v11
	v_div_fixup_f32 v4, v8, v5, v24
	ds_write_b32 v2, v4 offset:4
	s_waitcnt vmcnt(30)
	v_mul_f32_e32 v5, 0xbfb8aa3b, v25
	v_exp_f32_e32 v5, v5
	s_nop 0
	v_add_f32_e32 v5, 1.0, v5
	v_div_scale_f32 v8, s[14:15], v5, v5, v25
	v_rcp_f32_e32 v9, v8
	s_nop 0
	v_fma_f32 v10, -v8, v9, 1.0
	v_fmac_f32_e32 v9, v10, v9
	v_div_scale_f32 v10, vcc, v25, v5, v25
	v_mul_f32_e32 v11, v10, v9
	v_fma_f32 v12, -v8, v11, v10
	v_fmac_f32_e32 v11, v12, v9
	v_fma_f32 v8, -v8, v11, v10
	v_div_fmas_f32 v8, v8, v9, v11
	v_div_fixup_f32 v4, v8, v5, v25
	ds_write_b32 v2, v4 offset:18436
	s_waitcnt vmcnt(29)
	v_mul_f32_e32 v5, 0xbfb8aa3b, v26
	v_exp_f32_e32 v5, v5
	s_nop 0
	v_add_f32_e32 v5, 1.0, v5
	v_div_scale_f32 v8, s[14:15], v5, v5, v26
	v_rcp_f32_e32 v9, v8
	s_nop 0
	v_fma_f32 v10, -v8, v9, 1.0
	v_fmac_f32_e32 v9, v10, v9
	v_div_scale_f32 v10, vcc, v26, v5, v26
	v_mul_f32_e32 v11, v10, v9
	v_fma_f32 v12, -v8, v11, v10
	v_fmac_f32_e32 v11, v12, v9
	v_fma_f32 v8, -v8, v11, v10
	v_div_fmas_f32 v8, v8, v9, v11
	v_div_fixup_f32 v4, v8, v5, v26
	ds_write_b32 v2, v4 offset:36868
	s_waitcnt vmcnt(28)
	v_mul_f32_e32 v5, 0xbfb8aa3b, v27
	v_exp_f32_e32 v5, v5
	s_nop 0
	v_add_f32_e32 v5, 1.0, v5
	v_div_scale_f32 v8, s[14:15], v5, v5, v27
	v_rcp_f32_e32 v9, v8
	s_nop 0
	v_fma_f32 v10, -v8, v9, 1.0
	v_fmac_f32_e32 v9, v10, v9
	v_div_scale_f32 v10, vcc, v27, v5, v27
	v_mul_f32_e32 v11, v10, v9
	v_fma_f32 v12, -v8, v11, v10
	v_fmac_f32_e32 v11, v12, v9
	v_fma_f32 v8, -v8, v11, v10
	v_div_fmas_f32 v8, v8, v9, v11
	v_div_fixup_f32 v4, v8, v5, v27
	ds_write_b32 v2, v4 offset:55300
	s_waitcnt vmcnt(27)
	v_mul_f32_e32 v5, 0xbfb8aa3b, v28
	v_exp_f32_e32 v5, v5
	s_nop 0
	v_add_f32_e32 v5, 1.0, v5
	v_div_scale_f32 v8, s[14:15], v5, v5, v28
	v_rcp_f32_e32 v9, v8
	s_nop 0
	v_fma_f32 v10, -v8, v9, 1.0
	v_fmac_f32_e32 v9, v10, v9
	v_div_scale_f32 v10, vcc, v28, v5, v28
	v_mul_f32_e32 v11, v10, v9
	v_fma_f32 v12, -v8, v11, v10
	v_fmac_f32_e32 v11, v12, v9
	v_fma_f32 v8, -v8, v11, v10
	v_div_fmas_f32 v8, v8, v9, v11
	v_div_fixup_f32 v4, v8, v5, v28
	ds_write_b32 v2, v4 offset:8
	s_waitcnt vmcnt(26)
	v_mul_f32_e32 v5, 0xbfb8aa3b, v29
	v_exp_f32_e32 v5, v5
	s_nop 0
	v_add_f32_e32 v5, 1.0, v5
	v_div_scale_f32 v8, s[14:15], v5, v5, v29
	v_rcp_f32_e32 v9, v8
	s_nop 0
	v_fma_f32 v10, -v8, v9, 1.0
	v_fmac_f32_e32 v9, v10, v9
	v_div_scale_f32 v10, vcc, v29, v5, v29
	v_mul_f32_e32 v11, v10, v9
	v_fma_f32 v12, -v8, v11, v10
	v_fmac_f32_e32 v11, v12, v9
	v_fma_f32 v8, -v8, v11, v10
	v_div_fmas_f32 v8, v8, v9, v11
	v_div_fixup_f32 v4, v8, v5, v29
	ds_write_b32 v2, v4 offset:18440
	s_waitcnt vmcnt(25)
	v_mul_f32_e32 v5, 0xbfb8aa3b, v30
	v_exp_f32_e32 v5, v5
	s_nop 0
	v_add_f32_e32 v5, 1.0, v5
	v_div_scale_f32 v8, s[14:15], v5, v5, v30
	v_rcp_f32_e32 v9, v8
	s_nop 0
	v_fma_f32 v10, -v8, v9, 1.0
	v_fmac_f32_e32 v9, v10, v9
	v_div_scale_f32 v10, vcc, v30, v5, v30
	v_mul_f32_e32 v11, v10, v9
	v_fma_f32 v12, -v8, v11, v10
	v_fmac_f32_e32 v11, v12, v9
	v_fma_f32 v8, -v8, v11, v10
	v_div_fmas_f32 v8, v8, v9, v11
	v_div_fixup_f32 v4, v8, v5, v30
	ds_write_b32 v2, v4 offset:36872
	s_waitcnt vmcnt(24)
	v_mul_f32_e32 v5, 0xbfb8aa3b, v31
	v_exp_f32_e32 v5, v5
	s_nop 0
	v_add_f32_e32 v5, 1.0, v5
	v_div_scale_f32 v8, s[14:15], v5, v5, v31
	v_rcp_f32_e32 v9, v8
	s_nop 0
	v_fma_f32 v10, -v8, v9, 1.0
	v_fmac_f32_e32 v9, v10, v9
	v_div_scale_f32 v10, vcc, v31, v5, v31
	v_mul_f32_e32 v11, v10, v9
	v_fma_f32 v12, -v8, v11, v10
	v_fmac_f32_e32 v11, v12, v9
	v_fma_f32 v8, -v8, v11, v10
	v_div_fmas_f32 v8, v8, v9, v11
	v_div_fixup_f32 v4, v8, v5, v31
	ds_write_b32 v2, v4 offset:55304
	s_waitcnt vmcnt(23)
	v_mul_f32_e32 v5, 0xbfb8aa3b, v32
	v_exp_f32_e32 v5, v5
	s_nop 0
	v_add_f32_e32 v5, 1.0, v5
	v_div_scale_f32 v8, s[14:15], v5, v5, v32
	v_rcp_f32_e32 v9, v8
	s_nop 0
	v_fma_f32 v10, -v8, v9, 1.0
	v_fmac_f32_e32 v9, v10, v9
	v_div_scale_f32 v10, vcc, v32, v5, v32
	v_mul_f32_e32 v11, v10, v9
	v_fma_f32 v12, -v8, v11, v10
	v_fmac_f32_e32 v11, v12, v9
	v_fma_f32 v8, -v8, v11, v10
	v_div_fmas_f32 v8, v8, v9, v11
	v_div_fixup_f32 v4, v8, v5, v32
	ds_write_b32 v2, v4 offset:12
	s_waitcnt vmcnt(22)
	v_mul_f32_e32 v5, 0xbfb8aa3b, v33
	v_exp_f32_e32 v5, v5
	s_nop 0
	v_add_f32_e32 v5, 1.0, v5
	v_div_scale_f32 v8, s[14:15], v5, v5, v33
	v_rcp_f32_e32 v9, v8
	s_nop 0
	v_fma_f32 v10, -v8, v9, 1.0
	v_fmac_f32_e32 v9, v10, v9
	v_div_scale_f32 v10, vcc, v33, v5, v33
	v_mul_f32_e32 v11, v10, v9
	v_fma_f32 v12, -v8, v11, v10
	v_fmac_f32_e32 v11, v12, v9
	v_fma_f32 v8, -v8, v11, v10
	v_div_fmas_f32 v8, v8, v9, v11
	v_div_fixup_f32 v4, v8, v5, v33
	ds_write_b32 v2, v4 offset:18444
	s_waitcnt vmcnt(21)
	v_mul_f32_e32 v5, 0xbfb8aa3b, v34
	v_exp_f32_e32 v5, v5
	s_nop 0
	v_add_f32_e32 v5, 1.0, v5
	v_div_scale_f32 v8, s[14:15], v5, v5, v34
	v_rcp_f32_e32 v9, v8
	s_nop 0
	v_fma_f32 v10, -v8, v9, 1.0
	v_fmac_f32_e32 v9, v10, v9
	v_div_scale_f32 v10, vcc, v34, v5, v34
	v_mul_f32_e32 v11, v10, v9
	v_fma_f32 v12, -v8, v11, v10
	v_fmac_f32_e32 v11, v12, v9
	v_fma_f32 v8, -v8, v11, v10
	v_div_fmas_f32 v8, v8, v9, v11
	v_div_fixup_f32 v4, v8, v5, v34
	ds_write_b32 v2, v4 offset:36876
	s_waitcnt vmcnt(20)
; __device__ __forceinline__ void ada_phase(LAS unsigned char* lds, const float* c, const float* c_ctx, const float* ada_w, const float* ada_b, float* mods, int G, int bid, int tid, int item0, int item1) {
;     ...
;     for (int idx = tid; idx < 9 * D; idx += NTHR) { const int r = idx / D, k = idx % D; const float v = (r < 8) ? c[r * D + k] : c_ctx[k]; sT[k * 9 + r] = v / (1.0f + __expf(-v)); }
	v_mul_f32_e32 v5, 0xbfb8aa3b, v35
	v_exp_f32_e32 v5, v5
	s_nop 0
	v_add_f32_e32 v5, 1.0, v5
	v_div_scale_f32 v8, s[14:15], v5, v5, v35
	v_rcp_f32_e32 v9, v8
	s_nop 0
	v_fma_f32 v10, -v8, v9, 1.0
	v_fmac_f32_e32 v9, v10, v9
	v_div_scale_f32 v10, vcc, v35, v5, v35
	v_mul_f32_e32 v11, v10, v9
	v_fma_f32 v12, -v8, v11, v10
	v_fmac_f32_e32 v11, v12, v9
	v_fma_f32 v8, -v8, v11, v10
	v_div_fmas_f32 v8, v8, v9, v11
	v_div_fixup_f32 v4, v8, v5, v35
	ds_write_b32 v2, v4 offset:55308
	s_waitcnt vmcnt(19)
	v_mul_f32_e32 v5, 0xbfb8aa3b, v36
	v_exp_f32_e32 v5, v5
	s_nop 0
	v_add_f32_e32 v5, 1.0, v5
	v_div_scale_f32 v8, s[14:15], v5, v5, v36
	v_rcp_f32_e32 v9, v8
	s_nop 0
	v_fma_f32 v10, -v8, v9, 1.0
	v_fmac_f32_e32 v9, v10, v9
	v_div_scale_f32 v10, vcc, v36, v5, v36
	v_mul_f32_e32 v11, v10, v9
	v_fma_f32 v12, -v8, v11, v10
	v_fmac_f32_e32 v11, v12, v9
	v_fma_f32 v8, -v8, v11, v10
	v_div_fmas_f32 v8, v8, v9, v11
	v_div_fixup_f32 v4, v8, v5, v36
	ds_write_b32 v2, v4 offset:16
	s_waitcnt vmcnt(18)
	v_mul_f32_e32 v5, 0xbfb8aa3b, v37
	v_exp_f32_e32 v5, v5
	s_nop 0
	v_add_f32_e32 v5, 1.0, v5
	v_div_scale_f32 v8, s[14:15], v5, v5, v37
	v_rcp_f32_e32 v9, v8
	s_nop 0
	v_fma_f32 v10, -v8, v9, 1.0
	v_fmac_f32_e32 v9, v10, v9
	v_div_scale_f32 v10, vcc, v37, v5, v37
	v_mul_f32_e32 v11, v10, v9
	v_fma_f32 v12, -v8, v11, v10
	v_fmac_f32_e32 v11, v12, v9
	v_fma_f32 v8, -v8, v11, v10
	v_div_fmas_f32 v8, v8, v9, v11
	v_div_fixup_f32 v4, v8, v5, v37
	ds_write_b32 v2, v4 offset:18448
	s_waitcnt vmcnt(17)
	v_mul_f32_e32 v5, 0xbfb8aa3b, v38
	v_exp_f32_e32 v5, v5
	s_nop 0
	v_add_f32_e32 v5, 1.0, v5
	v_div_scale_f32 v8, s[14:15], v5, v5, v38
	v_rcp_f32_e32 v9, v8
	s_nop 0
	v_fma_f32 v10, -v8, v9, 1.0
	v_fmac_f32_e32 v9, v10, v9
	v_div_scale_f32 v10, vcc, v38, v5, v38
	v_mul_f32_e32 v11, v10, v9
	v_fma_f32 v12, -v8, v11, v10
	v_fmac_f32_e32 v11, v12, v9
	v_fma_f32 v8, -v8, v11, v10
	v_div_fmas_f32 v8, v8, v9, v11
	v_div_fixup_f32 v4, v8, v5, v38
	ds_write_b32 v2, v4 offset:36880
	s_waitcnt vmcnt(16)
	v_mul_f32_e32 v5, 0xbfb8aa3b, v39
	v_exp_f32_e32 v5, v5
	s_nop 0
	v_add_f32_e32 v5, 1.0, v5
	v_div_scale_f32 v8, s[14:15], v5, v5, v39
	v_rcp_f32_e32 v9, v8
	s_nop 0
	v_fma_f32 v10, -v8, v9, 1.0
	v_fmac_f32_e32 v9, v10, v9
	v_div_scale_f32 v10, vcc, v39, v5, v39
	v_mul_f32_e32 v11, v10, v9
	v_fma_f32 v12, -v8, v11, v10
	v_fmac_f32_e32 v11, v12, v9
	v_fma_f32 v8, -v8, v11, v10
	v_div_fmas_f32 v8, v8, v9, v11
	v_div_fixup_f32 v4, v8, v5, v39
	ds_write_b32 v2, v4 offset:55312
	s_waitcnt vmcnt(15)
	v_mul_f32_e32 v5, 0xbfb8aa3b, v40
	v_exp_f32_e32 v5, v5
	s_nop 0
	v_add_f32_e32 v5, 1.0, v5
	v_div_scale_f32 v8, s[14:15], v5, v5, v40
	v_rcp_f32_e32 v9, v8
	s_nop 0
	v_fma_f32 v10, -v8, v9, 1.0
	v_fmac_f32_e32 v9, v10, v9
	v_div_scale_f32 v10, vcc, v40, v5, v40
	v_mul_f32_e32 v11, v10, v9
	v_fma_f32 v12, -v8, v11, v10
	v_fmac_f32_e32 v11, v12, v9
	v_fma_f32 v8, -v8, v11, v10
	v_div_fmas_f32 v8, v8, v9, v11
	v_div_fixup_f32 v4, v8, v5, v40
	ds_write_b32 v2, v4 offset:20
	s_waitcnt vmcnt(14)
	v_mul_f32_e32 v5, 0xbfb8aa3b, v41
	v_exp_f32_e32 v5, v5
	s_nop 0
	v_add_f32_e32 v5, 1.0, v5
	v_div_scale_f32 v8, s[14:15], v5, v5, v41
	v_rcp_f32_e32 v9, v8
	s_nop 0
	v_fma_f32 v10, -v8, v9, 1.0
	v_fmac_f32_e32 v9, v10, v9
	v_div_scale_f32 v10, vcc, v41, v5, v41
	v_mul_f32_e32 v11, v10, v9
	v_fma_f32 v12, -v8, v11, v10
	v_fmac_f32_e32 v11, v12, v9
	v_fma_f32 v8, -v8, v11, v10
	v_div_fmas_f32 v8, v8, v9, v11
	v_div_fixup_f32 v4, v8, v5, v41
	ds_write_b32 v2, v4 offset:18452
	s_waitcnt vmcnt(13)
	v_mul_f32_e32 v5, 0xbfb8aa3b, v42
	v_exp_f32_e32 v5, v5
	s_nop 0
	v_add_f32_e32 v5, 1.0, v5
	v_div_scale_f32 v8, s[14:15], v5, v5, v42
	v_rcp_f32_e32 v9, v8
	s_nop 0
	v_fma_f32 v10, -v8, v9, 1.0
	v_fmac_f32_e32 v9, v10, v9
	v_div_scale_f32 v10, vcc, v42, v5, v42
	v_mul_f32_e32 v11, v10, v9
	v_fma_f32 v12, -v8, v11, v10
	v_fmac_f32_e32 v11, v12, v9
	v_fma_f32 v8, -v8, v11, v10
	v_div_fmas_f32 v8, v8, v9, v11
	v_div_fixup_f32 v4, v8, v5, v42
	ds_write_b32 v2, v4 offset:36884
	s_waitcnt vmcnt(12)
	v_mul_f32_e32 v5, 0xbfb8aa3b, v43
	v_exp_f32_e32 v5, v5
	s_nop 0
	v_add_f32_e32 v5, 1.0, v5
	v_div_scale_f32 v8, s[14:15], v5, v5, v43
	v_rcp_f32_e32 v9, v8
	s_nop 0
	v_fma_f32 v10, -v8, v9, 1.0
	v_fmac_f32_e32 v9, v10, v9
	v_div_scale_f32 v10, vcc, v43, v5, v43
	v_mul_f32_e32 v11, v10, v9
	v_fma_f32 v12, -v8, v11, v10
	v_fmac_f32_e32 v11, v12, v9
	v_fma_f32 v8, -v8, v11, v10
	v_div_fmas_f32 v8, v8, v9, v11
	v_div_fixup_f32 v4, v8, v5, v43
	ds_write_b32 v2, v4 offset:55316
	s_waitcnt vmcnt(11)
	v_mul_f32_e32 v5, 0xbfb8aa3b, v44
	v_exp_f32_e32 v5, v5
	s_nop 0
	v_add_f32_e32 v5, 1.0, v5
	v_div_scale_f32 v8, s[14:15], v5, v5, v44
	v_rcp_f32_e32 v9, v8
	s_nop 0
	v_fma_f32 v10, -v8, v9, 1.0
	v_fmac_f32_e32 v9, v10, v9
	v_div_scale_f32 v10, vcc, v44, v5, v44
	v_mul_f32_e32 v11, v10, v9
	v_fma_f32 v12, -v8, v11, v10
	v_fmac_f32_e32 v11, v12, v9
	v_fma_f32 v8, -v8, v11, v10
	v_div_fmas_f32 v8, v8, v9, v11
	v_div_fixup_f32 v4, v8, v5, v44
	ds_write_b32 v2, v4 offset:24
	s_waitcnt vmcnt(10)
; __device__ __forceinline__ void ada_phase(LAS unsigned char* lds, const float* c, const float* c_ctx, const float* ada_w, const float* ada_b, float* mods, int G, int bid, int tid, int item0, int item1) {
;     ...
;     for (int idx = tid; idx < 9 * D; idx += NTHR) { const int r = idx / D, k = idx % D; const float v = (r < 8) ? c[r * D + k] : c_ctx[k]; sT[k * 9 + r] = v / (1.0f + __expf(-v)); }
	v_mul_f32_e32 v5, 0xbfb8aa3b, v45
	v_exp_f32_e32 v5, v5
	s_nop 0
	v_add_f32_e32 v5, 1.0, v5
	v_div_scale_f32 v8, s[14:15], v5, v5, v45
	v_rcp_f32_e32 v9, v8
	s_nop 0
	v_fma_f32 v10, -v8, v9, 1.0
	v_fmac_f32_e32 v9, v10, v9
	v_div_scale_f32 v10, vcc, v45, v5, v45
	v_mul_f32_e32 v11, v10, v9
	v_fma_f32 v12, -v8, v11, v10
	v_fmac_f32_e32 v11, v12, v9
	v_fma_f32 v8, -v8, v11, v10
	v_div_fmas_f32 v8, v8, v9, v11
	v_div_fixup_f32 v4, v8, v5, v45
	ds_write_b32 v2, v4 offset:18456
	s_waitcnt vmcnt(9)
	v_mul_f32_e32 v5, 0xbfb8aa3b, v46
	v_exp_f32_e32 v5, v5
	s_nop 0
	v_add_f32_e32 v5, 1.0, v5
	v_div_scale_f32 v8, s[14:15], v5, v5, v46
	v_rcp_f32_e32 v9, v8
	s_nop 0
	v_fma_f32 v10, -v8, v9, 1.0
	v_fmac_f32_e32 v9, v10, v9
	v_div_scale_f32 v10, vcc, v46, v5, v46
	v_mul_f32_e32 v11, v10, v9
	v_fma_f32 v12, -v8, v11, v10
	v_fmac_f32_e32 v11, v12, v9
	v_fma_f32 v8, -v8, v11, v10
	v_div_fmas_f32 v8, v8, v9, v11
	v_div_fixup_f32 v4, v8, v5, v46
	ds_write_b32 v2, v4 offset:36888
	s_waitcnt vmcnt(8)
	v_mul_f32_e32 v5, 0xbfb8aa3b, v47
	v_exp_f32_e32 v5, v5
	s_nop 0
	v_add_f32_e32 v5, 1.0, v5
	v_div_scale_f32 v8, s[14:15], v5, v5, v47
	v_rcp_f32_e32 v9, v8
	s_nop 0
	v_fma_f32 v10, -v8, v9, 1.0
	v_fmac_f32_e32 v9, v10, v9
	v_div_scale_f32 v10, vcc, v47, v5, v47
	v_mul_f32_e32 v11, v10, v9
	v_fma_f32 v12, -v8, v11, v10
	v_fmac_f32_e32 v11, v12, v9
	v_fma_f32 v8, -v8, v11, v10
	v_div_fmas_f32 v8, v8, v9, v11
	v_div_fixup_f32 v4, v8, v5, v47
	ds_write_b32 v2, v4 offset:55320
	s_waitcnt vmcnt(7)
	v_mul_f32_e32 v5, 0xbfb8aa3b, v48
	v_exp_f32_e32 v5, v5
	s_nop 0
	v_add_f32_e32 v5, 1.0, v5
	v_div_scale_f32 v8, s[14:15], v5, v5, v48
	v_rcp_f32_e32 v9, v8
	s_nop 0
	v_fma_f32 v10, -v8, v9, 1.0
	v_fmac_f32_e32 v9, v10, v9
	v_div_scale_f32 v10, vcc, v48, v5, v48
	v_mul_f32_e32 v11, v10, v9
	v_fma_f32 v12, -v8, v11, v10
	v_fmac_f32_e32 v11, v12, v9
	v_fma_f32 v8, -v8, v11, v10
	v_div_fmas_f32 v8, v8, v9, v11
	v_div_fixup_f32 v4, v8, v5, v48
	ds_write_b32 v2, v4 offset:28
	s_waitcnt vmcnt(6)
	v_mul_f32_e32 v5, 0xbfb8aa3b, v49
	v_exp_f32_e32 v5, v5
	s_nop 0
	v_add_f32_e32 v5, 1.0, v5
	v_div_scale_f32 v8, s[14:15], v5, v5, v49
	v_rcp_f32_e32 v9, v8
	s_nop 0
	v_fma_f32 v10, -v8, v9, 1.0
	v_fmac_f32_e32 v9, v10, v9
	v_div_scale_f32 v10, vcc, v49, v5, v49
	v_mul_f32_e32 v11, v10, v9
	v_fma_f32 v12, -v8, v11, v10
	v_fmac_f32_e32 v11, v12, v9
	v_fma_f32 v8, -v8, v11, v10
	v_div_fmas_f32 v8, v8, v9, v11
	v_div_fixup_f32 v4, v8, v5, v49
	ds_write_b32 v2, v4 offset:18460
	s_waitcnt vmcnt(5)
	v_mul_f32_e32 v5, 0xbfb8aa3b, v50
	v_exp_f32_e32 v5, v5
	s_nop 0
	v_add_f32_e32 v5, 1.0, v5
	v_div_scale_f32 v8, s[14:15], v5, v5, v50
	v_rcp_f32_e32 v9, v8
	s_nop 0
	v_fma_f32 v10, -v8, v9, 1.0
	v_fmac_f32_e32 v9, v10, v9
	v_div_scale_f32 v10, vcc, v50, v5, v50
	v_mul_f32_e32 v11, v10, v9
	v_fma_f32 v12, -v8, v11, v10
	v_fmac_f32_e32 v11, v12, v9
	v_fma_f32 v8, -v8, v11, v10
	v_div_fmas_f32 v8, v8, v9, v11
	v_div_fixup_f32 v4, v8, v5, v50
	ds_write_b32 v2, v4 offset:36892
	s_waitcnt vmcnt(4)
	v_mul_f32_e32 v5, 0xbfb8aa3b, v51
	v_exp_f32_e32 v5, v5
	s_nop 0
	v_add_f32_e32 v5, 1.0, v5
	v_div_scale_f32 v8, s[14:15], v5, v5, v51
	v_rcp_f32_e32 v9, v8
	s_nop 0
	v_fma_f32 v10, -v8, v9, 1.0
	v_fmac_f32_e32 v9, v10, v9
	v_div_scale_f32 v10, vcc, v51, v5, v51
	v_mul_f32_e32 v11, v10, v9
	v_fma_f32 v12, -v8, v11, v10
	v_fmac_f32_e32 v11, v12, v9
	v_fma_f32 v8, -v8, v11, v10
	v_div_fmas_f32 v8, v8, v9, v11
	v_div_fixup_f32 v4, v8, v5, v51
	ds_write_b32 v2, v4 offset:55324
	s_waitcnt vmcnt(3)
	v_mul_f32_e32 v5, 0xbfb8aa3b, v52
	v_exp_f32_e32 v5, v5
	s_nop 0
	v_add_f32_e32 v5, 1.0, v5
	v_div_scale_f32 v8, s[14:15], v5, v5, v52
	v_rcp_f32_e32 v9, v8
	s_nop 0
	v_fma_f32 v10, -v8, v9, 1.0
	v_fmac_f32_e32 v9, v10, v9
	v_div_scale_f32 v10, vcc, v52, v5, v52
	v_mul_f32_e32 v11, v10, v9
	v_fma_f32 v12, -v8, v11, v10
	v_fmac_f32_e32 v11, v12, v9
	v_fma_f32 v8, -v8, v11, v10
	v_div_fmas_f32 v8, v8, v9, v11
	v_div_fixup_f32 v4, v8, v5, v52
	ds_write_b32 v2, v4 offset:32
	s_waitcnt vmcnt(2)
	v_mul_f32_e32 v5, 0xbfb8aa3b, v53
	v_exp_f32_e32 v5, v5
	s_nop 0
	v_add_f32_e32 v5, 1.0, v5
	v_div_scale_f32 v8, s[14:15], v5, v5, v53
	v_rcp_f32_e32 v9, v8
	s_nop 0
	v_fma_f32 v10, -v8, v9, 1.0
	v_fmac_f32_e32 v9, v10, v9
	v_div_scale_f32 v10, vcc, v53, v5, v53
	v_mul_f32_e32 v11, v10, v9
	v_fma_f32 v12, -v8, v11, v10
	v_fmac_f32_e32 v11, v12, v9
	v_fma_f32 v8, -v8, v11, v10
	v_div_fmas_f32 v8, v8, v9, v11
	v_div_fixup_f32 v4, v8, v5, v53
	ds_write_b32 v2, v4 offset:18464
	s_waitcnt vmcnt(1)
	v_mul_f32_e32 v5, 0xbfb8aa3b, v54
	v_exp_f32_e32 v5, v5
	s_nop 0
	v_add_f32_e32 v5, 1.0, v5
	v_div_scale_f32 v8, s[14:15], v5, v5, v54
	v_rcp_f32_e32 v9, v8
	s_nop 0
	v_fma_f32 v10, -v8, v9, 1.0
	v_fmac_f32_e32 v9, v10, v9
	v_div_scale_f32 v10, vcc, v54, v5, v54
	v_mul_f32_e32 v11, v10, v9
	v_fma_f32 v12, -v8, v11, v10
	v_fmac_f32_e32 v11, v12, v9
	v_fma_f32 v8, -v8, v11, v10
	v_div_fmas_f32 v8, v8, v9, v11
	v_div_fixup_f32 v4, v8, v5, v54
	ds_write_b32 v2, v4 offset:36896
	s_waitcnt vmcnt(0)
	v_mul_f32_e32 v5, 0xbfb8aa3b, v55
	v_exp_f32_e32 v5, v5
	s_nop 0
	v_add_f32_e32 v5, 1.0, v5
	v_div_scale_f32 v8, s[14:15], v5, v5, v55
	v_rcp_f32_e32 v9, v8
	s_nop 0
	v_fma_f32 v10, -v8, v9, 1.0
	v_fmac_f32_e32 v9, v10, v9
	v_div_scale_f32 v10, vcc, v55, v5, v55
	v_mul_f32_e32 v11, v10, v9
	v_fma_f32 v12, -v8, v11, v10
	v_fmac_f32_e32 v11, v12, v9
	v_fma_f32 v8, -v8, v11, v10
	v_div_fmas_f32 v8, v8, v9, v11
	v_div_fixup_f32 v4, v8, v5, v55
	ds_write_b32 v2, v4 offset:55328
